# GEMM main-loop heads padded to 8-byte alignment (s_nop before 4 of the 7 loop labels); on top of CONV5+S10
# baseline (speedup 1.0000x reference)
; template <class Epi, class Sched>
; __device__ __forceinline__ void gemm_phase(PG8_LAS unsigned char* lds, const Gemm g, const Sched& S, const Epi& E, int tid_in) {
;     ...
;         const bool has_next = S.next(ui + 1, nxt);
;         const char* nA = has_next ? (const char*)g.A + (size_t)nxt.pm * tstep : cA; const char* nB = has_next ? (const char*)g.Bt + (size_t)nxt.pn * tstep : cB;
;         for (int t = 0; t < nt; t += 2) {
;             const bool last = (t == nt - 2);
;             const char* a1 = cA + (size_t)(t + 1) * kstep;
;             const char* a2 = last ? nA : cA + (size_t)(t + 2) * kstep; const char* b2 = last ? nB : cB + (size_t)(t + 2) * kstep;
;     ...
; #pragma unroll
;         for (int a = 0; a < 2; ++a)
; #pragma unroll
;             for (int b = 0; b < 2; ++b)
; #pragma unroll
;                 for (int m = 0; m < 4; ++m)
; #pragma unroll
;                     for (int n = 0; n < 2; ++n) acc[a][b][m][n] = (f32x4){0.f, 0.f, 0.f, 0.f};
;         cur = nxt; cA = nA; cB = nB; ++ui;
.LBB0_265:
	s_ashr_i32 s15, s14, 31
	v_cmp_lt_i64_e32 vcc, s[22:23], v[242:243]
	s_lshl_b64 s[22:23], s[14:15], 21
	s_add_u32 s22, s38, s22
	s_addc_u32 s23, s39, s23
	s_and_b64 s[24:25], vcc, exec
	s_cselect_b32 s15, s23, s5
	s_cselect_b32 s52, s22, s4
	s_ashr_i32 s13, s12, 31
	s_lshl_b64 s[24:25], s[12:13], 21
	s_add_u32 s24, s40, s24
	s_addc_u32 s25, s41, s25
	s_and_b64 s[30:31], vcc, exec
	s_cselect_b32 s13, s25, s29
	s_cselect_b32 s53, s24, s28
	s_add_u32 s54, s28, 0x100
	v_mov_b32_e32 v0, 0
	s_addc_u32 s55, s29, 0
	s_mov_b32 s56, -2
	v_mov_b32_e32 v1, v0
	v_mov_b32_e32 v2, v0
	v_mov_b32_e32 v3, v0
	v_mov_b32_e32 v24, v0
	v_mov_b32_e32 v25, v0
	v_mov_b32_e32 v26, v0
	v_mov_b32_e32 v27, v0
	v_mov_b32_e32 v4, v0
	v_mov_b32_e32 v5, v0
	v_mov_b32_e32 v6, v0
	v_mov_b32_e32 v7, v0
	v_mov_b32_e32 v32, v0
	v_mov_b32_e32 v33, v0
	v_mov_b32_e32 v34, v0
	v_mov_b32_e32 v35, v0
	v_mov_b32_e32 v8, v0
	v_mov_b32_e32 v9, v0
	v_mov_b32_e32 v10, v0
	v_mov_b32_e32 v11, v0
	v_mov_b32_e32 v40, v0
	v_mov_b32_e32 v41, v0
	v_mov_b32_e32 v42, v0
	v_mov_b32_e32 v43, v0
	v_mov_b32_e32 v12, v0
	v_mov_b32_e32 v13, v0
	v_mov_b32_e32 v14, v0
	v_mov_b32_e32 v15, v0
	v_mov_b32_e32 v44, v0
	v_mov_b32_e32 v45, v0
	v_mov_b32_e32 v46, v0
	v_mov_b32_e32 v47, v0
	v_mov_b32_e32 v60, v0
	v_mov_b32_e32 v61, v0
	v_mov_b32_e32 v62, v0
	v_mov_b32_e32 v63, v0
	v_mov_b32_e32 v92, v0
	v_mov_b32_e32 v93, v0
	v_mov_b32_e32 v94, v0
	v_mov_b32_e32 v95, v0
	v_mov_b32_e32 v68, v0
	v_mov_b32_e32 v69, v0
	v_mov_b32_e32 v70, v0
	v_mov_b32_e32 v71, v0
	v_mov_b32_e32 v100, v0
	v_mov_b32_e32 v101, v0
	v_mov_b32_e32 v102, v0
	v_mov_b32_e32 v103, v0
	v_mov_b32_e32 v72, v0
	v_mov_b32_e32 v73, v0
	v_mov_b32_e32 v74, v0
	v_mov_b32_e32 v75, v0
	v_mov_b32_e32 v104, v0
	v_mov_b32_e32 v105, v0
	v_mov_b32_e32 v106, v0
	v_mov_b32_e32 v107, v0
	v_mov_b32_e32 v76, v0
	v_mov_b32_e32 v77, v0
	v_mov_b32_e32 v78, v0
	v_mov_b32_e32 v79, v0
	v_mov_b32_e32 v108, v0
	v_mov_b32_e32 v109, v0
	v_mov_b32_e32 v110, v0
	v_mov_b32_e32 v111, v0
	v_mov_b32_e32 v16, v0
	v_mov_b32_e32 v17, v0
	v_mov_b32_e32 v18, v0
	v_mov_b32_e32 v19, v0
	v_mov_b32_e32 v48, v0
	v_mov_b32_e32 v49, v0
	v_mov_b32_e32 v50, v0
	v_mov_b32_e32 v51, v0
	v_mov_b32_e32 v20, v0
	v_mov_b32_e32 v21, v0
	v_mov_b32_e32 v22, v0
	v_mov_b32_e32 v23, v0
	v_mov_b32_e32 v52, v0
	v_mov_b32_e32 v53, v0
	v_mov_b32_e32 v54, v0
	v_mov_b32_e32 v55, v0
	v_mov_b32_e32 v28, v0
	v_mov_b32_e32 v29, v0
	v_mov_b32_e32 v30, v0
	v_mov_b32_e32 v31, v0
	v_mov_b32_e32 v56, v0
	v_mov_b32_e32 v57, v0
	v_mov_b32_e32 v58, v0
	v_mov_b32_e32 v59, v0
	v_mov_b32_e32 v36, v0
	v_mov_b32_e32 v37, v0
	v_mov_b32_e32 v38, v0
	v_mov_b32_e32 v39, v0
	v_mov_b32_e32 v64, v0
	v_mov_b32_e32 v65, v0
	v_mov_b32_e32 v66, v0
	v_mov_b32_e32 v67, v0
	v_mov_b32_e32 v80, v0
	v_mov_b32_e32 v81, v0
	v_mov_b32_e32 v82, v0
	v_mov_b32_e32 v83, v0
	v_mov_b32_e32 v112, v0
	v_mov_b32_e32 v113, v0
	v_mov_b32_e32 v114, v0
	v_mov_b32_e32 v115, v0
	v_mov_b32_e32 v84, v0
	v_mov_b32_e32 v85, v0
	v_mov_b32_e32 v86, v0
	v_mov_b32_e32 v87, v0
	v_mov_b32_e32 v116, v0
	v_mov_b32_e32 v117, v0
	v_mov_b32_e32 v118, v0
	v_mov_b32_e32 v119, v0
	v_mov_b32_e32 v88, v0
	v_mov_b32_e32 v89, v0
	v_mov_b32_e32 v90, v0
	v_mov_b32_e32 v91, v0
	v_mov_b32_e32 v120, v0
	v_mov_b32_e32 v121, v0
	v_mov_b32_e32 v122, v0
	v_mov_b32_e32 v123, v0
	v_mov_b32_e32 v96, v0
	v_mov_b32_e32 v97, v0
	v_mov_b32_e32 v98, v0
	v_mov_b32_e32 v99, v0
	v_mov_b32_e32 v124, v0
	v_mov_b32_e32 v125, v0
	v_mov_b32_e32 v126, v0
	v_mov_b32_e32 v127, v0
	s_nop 0

; template <class Epi, class Sched>
; __device__ __forceinline__ void gemm_phase(PG8_LAS unsigned char* lds, const Gemm g, const Sched& S, const Epi& E, int tid_in) {
;     ...
;         const bool has_next = S.next(ui + 1, nxt);
;         const char* nA = has_next ? (const char*)g.A + (size_t)nxt.pm * tstep : cA; const char* nB = has_next ? (const char*)g.Bt + (size_t)nxt.pn * tstep : cB;
;         for (int t = 0; t < nt; t += 2) {
;             const bool last = (t == nt - 2);
;             const char* a1 = cA + (size_t)(t + 1) * kstep;
;             const char* a2 = last ? nA : cA + (size_t)(t + 2) * kstep; const char* b2 = last ? nB : cB + (size_t)(t + 2) * kstep;
;     ...
; #pragma unroll
;         for (int a = 0; a < 2; ++a)
; #pragma unroll
;             for (int b = 0; b < 2; ++b)
; #pragma unroll
;                 for (int m = 0; m < 4; ++m)
; #pragma unroll
;                     for (int n = 0; n < 2; ++n) acc[a][b][m][n] = (f32x4){0.f, 0.f, 0.f, 0.f};
;         cur = nxt; cA = nA; cB = nB; ++ui;
.LBB0_369:
	s_ashr_i32 s11, s10, 31
	v_cmp_lt_i64_e32 vcc, s[12:13], v[242:243]
	s_lshl_b64 s[12:13], s[10:11], 19
	s_add_u32 s12, s26, s12
	s_addc_u32 s13, s27, s13
	s_and_b64 s[14:15], vcc, exec
	s_cselect_b32 s11, s13, s19
	s_cselect_b32 s41, s12, s18
	s_ashr_i32 s9, s8, 31
	s_lshl_b64 s[14:15], s[8:9], 19
	s_add_u32 s14, s28, s14
	s_addc_u32 s15, s29, s15
	s_and_b64 s[22:23], vcc, exec
	s_cselect_b32 s9, s15, s21
	s_cselect_b32 s42, s14, s20
	s_add_u32 s18, s18, 0x40080
	s_addc_u32 s19, s19, 0
	s_add_u32 s43, s20, 0x100
	v_mov_b32_e32 v0, 0
	s_addc_u32 s44, s21, 0
	s_mov_b32 s45, -2
	v_mov_b32_e32 v1, v0
	v_mov_b32_e32 v2, v0
	v_mov_b32_e32 v3, v0
	v_mov_b32_e32 v4, v0
	v_mov_b32_e32 v5, v0
	v_mov_b32_e32 v6, v0
	v_mov_b32_e32 v7, v0
	v_mov_b32_e32 v16, v0
	v_mov_b32_e32 v17, v0
	v_mov_b32_e32 v18, v0
	v_mov_b32_e32 v19, v0
	v_mov_b32_e32 v20, v0
	v_mov_b32_e32 v21, v0
	v_mov_b32_e32 v22, v0
	v_mov_b32_e32 v23, v0
	v_mov_b32_e32 v32, v0
	v_mov_b32_e32 v33, v0
	v_mov_b32_e32 v34, v0
	v_mov_b32_e32 v35, v0
	v_mov_b32_e32 v36, v0
	v_mov_b32_e32 v37, v0
	v_mov_b32_e32 v38, v0
	v_mov_b32_e32 v39, v0
	v_mov_b32_e32 v48, v0
	v_mov_b32_e32 v49, v0
	v_mov_b32_e32 v50, v0
	v_mov_b32_e32 v51, v0
	v_mov_b32_e32 v52, v0
	v_mov_b32_e32 v53, v0
	v_mov_b32_e32 v54, v0
	v_mov_b32_e32 v55, v0
	v_mov_b32_e32 v8, v0
	v_mov_b32_e32 v9, v0
	v_mov_b32_e32 v10, v0
	v_mov_b32_e32 v11, v0
	v_mov_b32_e32 v12, v0
	v_mov_b32_e32 v13, v0
	v_mov_b32_e32 v14, v0
	v_mov_b32_e32 v15, v0
	v_mov_b32_e32 v24, v0
	v_mov_b32_e32 v25, v0
	v_mov_b32_e32 v26, v0
	v_mov_b32_e32 v27, v0
	v_mov_b32_e32 v28, v0
	v_mov_b32_e32 v29, v0
	v_mov_b32_e32 v30, v0
	v_mov_b32_e32 v31, v0
	v_mov_b32_e32 v40, v0
	v_mov_b32_e32 v41, v0
	v_mov_b32_e32 v42, v0
	v_mov_b32_e32 v43, v0
	v_mov_b32_e32 v44, v0
	v_mov_b32_e32 v45, v0
	v_mov_b32_e32 v46, v0
	v_mov_b32_e32 v47, v0
	v_mov_b32_e32 v56, v0
	v_mov_b32_e32 v57, v0
	v_mov_b32_e32 v58, v0
	v_mov_b32_e32 v59, v0
	v_mov_b32_e32 v60, v0
	v_mov_b32_e32 v61, v0
	v_mov_b32_e32 v62, v0
	v_mov_b32_e32 v63, v0
	v_mov_b32_e32 v64, v0
	v_mov_b32_e32 v65, v0
	v_mov_b32_e32 v66, v0
	v_mov_b32_e32 v67, v0
	v_mov_b32_e32 v68, v0
	v_mov_b32_e32 v69, v0
	v_mov_b32_e32 v70, v0
	v_mov_b32_e32 v71, v0
	v_mov_b32_e32 v80, v0
	v_mov_b32_e32 v81, v0
	v_mov_b32_e32 v82, v0
	v_mov_b32_e32 v83, v0
	v_mov_b32_e32 v84, v0
	v_mov_b32_e32 v85, v0
	v_mov_b32_e32 v86, v0
	v_mov_b32_e32 v87, v0
	v_mov_b32_e32 v96, v0
	v_mov_b32_e32 v97, v0
	v_mov_b32_e32 v98, v0
	v_mov_b32_e32 v99, v0
	v_mov_b32_e32 v100, v0
	v_mov_b32_e32 v101, v0
	v_mov_b32_e32 v102, v0
	v_mov_b32_e32 v103, v0
	v_mov_b32_e32 v112, v0
	v_mov_b32_e32 v113, v0
	v_mov_b32_e32 v114, v0
	v_mov_b32_e32 v115, v0
	v_mov_b32_e32 v116, v0
	v_mov_b32_e32 v117, v0
	v_mov_b32_e32 v118, v0
	v_mov_b32_e32 v119, v0
	v_mov_b32_e32 v72, v0
	v_mov_b32_e32 v73, v0
	v_mov_b32_e32 v74, v0
	v_mov_b32_e32 v75, v0
	v_mov_b32_e32 v76, v0
	v_mov_b32_e32 v77, v0
	v_mov_b32_e32 v78, v0
	v_mov_b32_e32 v79, v0
	v_mov_b32_e32 v88, v0
	v_mov_b32_e32 v89, v0
	v_mov_b32_e32 v90, v0
	v_mov_b32_e32 v91, v0
	v_mov_b32_e32 v92, v0
	v_mov_b32_e32 v93, v0
	v_mov_b32_e32 v94, v0
	v_mov_b32_e32 v95, v0
	v_mov_b32_e32 v104, v0
	v_mov_b32_e32 v105, v0
	v_mov_b32_e32 v106, v0
	v_mov_b32_e32 v107, v0
	v_mov_b32_e32 v108, v0
	v_mov_b32_e32 v109, v0
	v_mov_b32_e32 v110, v0
	v_mov_b32_e32 v111, v0
	v_mov_b32_e32 v120, v0
	v_mov_b32_e32 v121, v0
	v_mov_b32_e32 v122, v0
	v_mov_b32_e32 v123, v0
	v_mov_b32_e32 v124, v0
	v_mov_b32_e32 v125, v0
	v_mov_b32_e32 v126, v0
	v_mov_b32_e32 v127, v0
	s_nop 0

; template <class Epi, class Sched>
; __device__ __forceinline__ void gemm_phase(PG8_LAS unsigned char* lds, const Gemm g, const Sched& S, const Epi& E, int tid_in) {
;     ...
;         const bool has_next = S.next(ui + 1, nxt);
;         const char* nA = has_next ? (const char*)g.A + (size_t)nxt.pm * tstep : cA; const char* nB = has_next ? (const char*)g.Bt + (size_t)nxt.pn * tstep : cB;
;         for (int t = 0; t < nt; t += 2) {
;             const bool last = (t == nt - 2);
;             const char* a1 = cA + (size_t)(t + 1) * kstep;
;             const char* a2 = last ? nA : cA + (size_t)(t + 2) * kstep; const char* b2 = last ? nB : cB + (size_t)(t + 2) * kstep;
;     ...
; #pragma unroll
;         for (int a = 0; a < 2; ++a)
; #pragma unroll
;             for (int b = 0; b < 2; ++b)
; #pragma unroll
;                 for (int m = 0; m < 4; ++m)
; #pragma unroll
;                     for (int n = 0; n < 2; ++n) acc[a][b][m][n] = (f32x4){0.f, 0.f, 0.f, 0.f};
;         cur = nxt; cA = nA; cB = nB; ++ui;
.LBB0_387:
	v_mov_b64_e32 v[0:1], 0xa00
	s_ashr_i32 s19, s18, 31
	v_cmp_lt_i64_e32 vcc, s[20:21], v[0:1]
	s_lshl_b64 s[20:21], s[18:19], 19
	s_add_u32 s20, s63, s20
	s_addc_u32 s21, s64, s21
	s_and_b64 s[22:23], vcc, exec
	s_cselect_b32 s1, s21, s27
	s_cselect_b32 s19, s20, s26
	s_ashr_i32 s17, s16, 31
	s_lshl_b64 s[22:23], s[16:17], 19
	s_add_u32 s22, s65, s22
	s_addc_u32 s23, s69, s23
	s_and_b64 s[30:31], vcc, exec
	s_cselect_b32 s17, s23, s29
	s_cselect_b32 s25, s22, s28
	s_add_u32 s26, s26, 0x40080
	s_addc_u32 s27, s27, 0
	s_add_u32 s33, s28, 0x100
	v_mov_b32_e32 v0, 0
	s_addc_u32 s36, s29, 0
	s_mov_b32 s37, -2
	v_mov_b32_e32 v1, v0
	v_mov_b32_e32 v2, v0
	v_mov_b32_e32 v3, v0
	v_mov_b32_e32 v4, v0
	v_mov_b32_e32 v5, v0
	v_mov_b32_e32 v6, v0
	v_mov_b32_e32 v7, v0
	v_mov_b32_e32 v16, v0
	v_mov_b32_e32 v17, v0
	v_mov_b32_e32 v18, v0
	v_mov_b32_e32 v19, v0
	v_mov_b32_e32 v20, v0
	v_mov_b32_e32 v21, v0
	v_mov_b32_e32 v22, v0
	v_mov_b32_e32 v23, v0
	v_mov_b32_e32 v32, v0
	v_mov_b32_e32 v33, v0
	v_mov_b32_e32 v34, v0
	v_mov_b32_e32 v35, v0
	v_mov_b32_e32 v36, v0
	v_mov_b32_e32 v37, v0
	v_mov_b32_e32 v38, v0
	v_mov_b32_e32 v39, v0
	v_mov_b32_e32 v48, v0
	v_mov_b32_e32 v49, v0
	v_mov_b32_e32 v50, v0
	v_mov_b32_e32 v51, v0
	v_mov_b32_e32 v52, v0
	v_mov_b32_e32 v53, v0
	v_mov_b32_e32 v54, v0
	v_mov_b32_e32 v55, v0
	v_mov_b32_e32 v8, v0
	v_mov_b32_e32 v9, v0
	v_mov_b32_e32 v10, v0
	v_mov_b32_e32 v11, v0
	v_mov_b32_e32 v12, v0
	v_mov_b32_e32 v13, v0
	v_mov_b32_e32 v14, v0
	v_mov_b32_e32 v15, v0
	v_mov_b32_e32 v24, v0
	v_mov_b32_e32 v25, v0
	v_mov_b32_e32 v26, v0
	v_mov_b32_e32 v27, v0
	v_mov_b32_e32 v28, v0
	v_mov_b32_e32 v29, v0
	v_mov_b32_e32 v30, v0
	v_mov_b32_e32 v31, v0
	v_mov_b32_e32 v40, v0
	v_mov_b32_e32 v41, v0
	v_mov_b32_e32 v42, v0
	v_mov_b32_e32 v43, v0
	v_mov_b32_e32 v44, v0
	v_mov_b32_e32 v45, v0
	v_mov_b32_e32 v46, v0
	v_mov_b32_e32 v47, v0
	v_mov_b32_e32 v56, v0
	v_mov_b32_e32 v57, v0
	v_mov_b32_e32 v58, v0
	v_mov_b32_e32 v59, v0
	v_mov_b32_e32 v60, v0
	v_mov_b32_e32 v61, v0
	v_mov_b32_e32 v62, v0
	v_mov_b32_e32 v63, v0
	v_mov_b32_e32 v64, v0
	v_mov_b32_e32 v65, v0
	v_mov_b32_e32 v66, v0
	v_mov_b32_e32 v67, v0
	v_mov_b32_e32 v68, v0
	v_mov_b32_e32 v69, v0
	v_mov_b32_e32 v70, v0
	v_mov_b32_e32 v71, v0
	v_mov_b32_e32 v80, v0
	v_mov_b32_e32 v81, v0
	v_mov_b32_e32 v82, v0
	v_mov_b32_e32 v83, v0
	v_mov_b32_e32 v84, v0
	v_mov_b32_e32 v85, v0
	v_mov_b32_e32 v86, v0
	v_mov_b32_e32 v87, v0
	v_mov_b32_e32 v96, v0
	v_mov_b32_e32 v97, v0
	v_mov_b32_e32 v98, v0
	v_mov_b32_e32 v99, v0
	v_mov_b32_e32 v100, v0
	v_mov_b32_e32 v101, v0
	v_mov_b32_e32 v102, v0
	v_mov_b32_e32 v103, v0
	v_mov_b32_e32 v112, v0
	v_mov_b32_e32 v113, v0
	v_mov_b32_e32 v114, v0
	v_mov_b32_e32 v115, v0
	v_mov_b32_e32 v116, v0
	v_mov_b32_e32 v117, v0
	v_mov_b32_e32 v118, v0
	v_mov_b32_e32 v119, v0
	v_mov_b32_e32 v72, v0
	v_mov_b32_e32 v73, v0
	v_mov_b32_e32 v74, v0
	v_mov_b32_e32 v75, v0
	v_mov_b32_e32 v76, v0
	v_mov_b32_e32 v77, v0
	v_mov_b32_e32 v78, v0
	v_mov_b32_e32 v79, v0
	v_mov_b32_e32 v88, v0
	v_mov_b32_e32 v89, v0
	v_mov_b32_e32 v90, v0
	v_mov_b32_e32 v91, v0
	v_mov_b32_e32 v92, v0
	v_mov_b32_e32 v93, v0
	v_mov_b32_e32 v94, v0
	v_mov_b32_e32 v95, v0
	v_mov_b32_e32 v104, v0
	v_mov_b32_e32 v105, v0
	v_mov_b32_e32 v106, v0
	v_mov_b32_e32 v107, v0
	v_mov_b32_e32 v108, v0
	v_mov_b32_e32 v109, v0
	v_mov_b32_e32 v110, v0
	v_mov_b32_e32 v111, v0
	s_waitcnt vmcnt(0)
	v_mov_b32_e32 v120, v0
	v_mov_b32_e32 v121, v0
	v_mov_b32_e32 v122, v0
	v_mov_b32_e32 v123, v0
	v_mov_b32_e32 v124, v0
	v_mov_b32_e32 v125, v0
	v_mov_b32_e32 v126, v0
	v_mov_b32_e32 v127, v0
	s_nop 0

; template <class Epi, class Sched>
; __device__ __forceinline__ void gemm_phase(PG8_LAS unsigned char* lds, const Gemm g, const Sched& S, const Epi& E, int tid_in) {
;     ...
;         const bool has_next = S.next(ui + 1, nxt);
;         const char* nA = has_next ? (const char*)g.A + (size_t)nxt.pm * tstep : cA; const char* nB = has_next ? (const char*)g.Bt + (size_t)nxt.pn * tstep : cB;
;         for (int t = 0; t < nt; t += 2) {
;             const bool last = (t == nt - 2);
;             const char* a1 = cA + (size_t)(t + 1) * kstep;
;             const char* a2 = last ? nA : cA + (size_t)(t + 2) * kstep; const char* b2 = last ? nB : cB + (size_t)(t + 2) * kstep;
;     ...
; #pragma unroll
;         for (int a = 0; a < 2; ++a)
; #pragma unroll
;             for (int b = 0; b < 2; ++b)
; #pragma unroll
;                 for (int m = 0; m < 4; ++m)
; #pragma unroll
;                     for (int n = 0; n < 2; ++n) acc[a][b][m][n] = (f32x4){0.f, 0.f, 0.f, 0.f};
;         cur = nxt; cA = nA; cB = nB; ++ui;
.LBB0_695:
	v_mov_b64_e32 v[0:1], 0xbd0
	s_ashr_i32 s11, s10, 31
	v_cmp_lt_i64_e32 vcc, s[12:13], v[0:1]
	s_lshl_b64 s[12:13], s[10:11], 19
	s_add_u32 s12, s23, s12
	s_addc_u32 s13, s24, s13
	s_and_b64 s[14:15], vcc, exec
	s_cselect_b32 s5, s13, s17
	s_cselect_b32 s7, s12, s16
	s_ashr_i32 s9, s8, 31
	s_lshl_b64 s[14:15], s[8:9], 19
	s_add_u32 s14, s25, s14
	s_addc_u32 s15, s26, s15
	s_and_b64 s[20:21], vcc, exec
	s_cselect_b32 s9, s15, s19
	s_cselect_b32 s11, s14, s18
	s_add_u32 s16, s16, 0x40080
	s_addc_u32 s17, s17, 0
	s_add_u32 s40, s18, 0x100
	v_mov_b32_e32 v0, 0
	s_addc_u32 s41, s19, 0
	s_mov_b32 s42, -2
	v_mov_b32_e32 v1, v0
	v_mov_b32_e32 v2, v0
	v_mov_b32_e32 v3, v0
	v_mov_b32_e32 v4, v0
	v_mov_b32_e32 v5, v0
	v_mov_b32_e32 v6, v0
	v_mov_b32_e32 v7, v0
	v_mov_b32_e32 v12, v0
	v_mov_b32_e32 v13, v0
	v_mov_b32_e32 v14, v0
	v_mov_b32_e32 v15, v0
	v_mov_b32_e32 v20, v0
	v_mov_b32_e32 v21, v0
	v_mov_b32_e32 v22, v0
	v_mov_b32_e32 v23, v0
	v_mov_b32_e32 v28, v0
	v_mov_b32_e32 v29, v0
	v_mov_b32_e32 v30, v0
	v_mov_b32_e32 v31, v0
	v_mov_b32_e32 v36, v0
	v_mov_b32_e32 v37, v0
	v_mov_b32_e32 v38, v0
	v_mov_b32_e32 v39, v0
	v_mov_b32_e32 v44, v0
	v_mov_b32_e32 v45, v0
	v_mov_b32_e32 v46, v0
	v_mov_b32_e32 v47, v0
	v_mov_b32_e32 v52, v0
	v_mov_b32_e32 v53, v0
	v_mov_b32_e32 v54, v0
	v_mov_b32_e32 v55, v0
	v_mov_b32_e32 v8, v0
	v_mov_b32_e32 v9, v0
	v_mov_b32_e32 v10, v0
	v_mov_b32_e32 v11, v0
	v_mov_b32_e32 v16, v0
	v_mov_b32_e32 v17, v0
	v_mov_b32_e32 v18, v0
	v_mov_b32_e32 v19, v0
	v_mov_b32_e32 v24, v0
	v_mov_b32_e32 v25, v0
	v_mov_b32_e32 v26, v0
	v_mov_b32_e32 v27, v0
	v_mov_b32_e32 v32, v0
	v_mov_b32_e32 v33, v0
	v_mov_b32_e32 v34, v0
	v_mov_b32_e32 v35, v0
	v_mov_b32_e32 v40, v0
	v_mov_b32_e32 v41, v0
	v_mov_b32_e32 v42, v0
	v_mov_b32_e32 v43, v0
	v_mov_b32_e32 v48, v0
	v_mov_b32_e32 v49, v0
	v_mov_b32_e32 v50, v0
	v_mov_b32_e32 v51, v0
	v_mov_b32_e32 v56, v0
	v_mov_b32_e32 v57, v0
	v_mov_b32_e32 v58, v0
	v_mov_b32_e32 v59, v0
	v_mov_b32_e32 v60, v0
	v_mov_b32_e32 v61, v0
	v_mov_b32_e32 v62, v0
	v_mov_b32_e32 v63, v0
	v_mov_b32_e32 v64, v0
	v_mov_b32_e32 v65, v0
	v_mov_b32_e32 v66, v0
	v_mov_b32_e32 v67, v0
	v_mov_b32_e32 v68, v0
	v_mov_b32_e32 v69, v0
	v_mov_b32_e32 v70, v0
	v_mov_b32_e32 v71, v0
	v_mov_b32_e32 v76, v0
	v_mov_b32_e32 v77, v0
	v_mov_b32_e32 v78, v0
	v_mov_b32_e32 v79, v0
	v_mov_b32_e32 v84, v0
	v_mov_b32_e32 v85, v0
	v_mov_b32_e32 v86, v0
	v_mov_b32_e32 v87, v0
	v_mov_b32_e32 v92, v0
	v_mov_b32_e32 v93, v0
	v_mov_b32_e32 v94, v0
	v_mov_b32_e32 v95, v0
	v_mov_b32_e32 v100, v0
	v_mov_b32_e32 v101, v0
	v_mov_b32_e32 v102, v0
	v_mov_b32_e32 v103, v0
	v_mov_b32_e32 v108, v0
	v_mov_b32_e32 v109, v0
	v_mov_b32_e32 v110, v0
	v_mov_b32_e32 v111, v0
	v_mov_b32_e32 v116, v0
	v_mov_b32_e32 v117, v0
	v_mov_b32_e32 v118, v0
	v_mov_b32_e32 v119, v0
	v_mov_b32_e32 v72, v0
	v_mov_b32_e32 v73, v0
	v_mov_b32_e32 v74, v0
	v_mov_b32_e32 v75, v0
	v_mov_b32_e32 v80, v0
	v_mov_b32_e32 v81, v0
	v_mov_b32_e32 v82, v0
	v_mov_b32_e32 v83, v0
	v_mov_b32_e32 v88, v0
	v_mov_b32_e32 v89, v0
	v_mov_b32_e32 v90, v0
	v_mov_b32_e32 v91, v0
	v_mov_b32_e32 v96, v0
	v_mov_b32_e32 v97, v0
	v_mov_b32_e32 v98, v0
	v_mov_b32_e32 v99, v0
	v_mov_b32_e32 v104, v0
	v_mov_b32_e32 v105, v0
	v_mov_b32_e32 v106, v0
	v_mov_b32_e32 v107, v0
	v_mov_b32_e32 v112, v0
	v_mov_b32_e32 v113, v0
	v_mov_b32_e32 v114, v0
	v_mov_b32_e32 v115, v0
	v_mov_b32_e32 v120, v0
	v_mov_b32_e32 v121, v0
	v_mov_b32_e32 v122, v0
	v_mov_b32_e32 v123, v0
	v_mov_b32_e32 v124, v0
	v_mov_b32_e32 v125, v0
	v_mov_b32_e32 v126, v0
	v_mov_b32_e32 v127, v0
	s_nop 0
